# gate/up GEMM prologue: the A-tile staging loads are issued before the wait for the row-scale partial sums (counted vmcnt(8) instead of vmcnt(0))
# baseline (speedup 1.0000x reference)
; #define PG8_STAGE(bufoff, gbase, voff) do { _Pragma("unroll") for (int _i = 0; _i < 2; ++_i) \
;         __builtin_amdgcn_global_load_lds((const unsigned*)((const char*)(gbase) + (voff)[_i]), (PG8_LAS unsigned*)(lds + (bufoff) + ldsw + _i * 8192), 16, 0, 0); } while (0)
; __device__ __forceinline__ void row_rs8(const float* ssq, int row0, int fq, float (&rr)[2][4]) {
;     float v[2][4][4];
; #pragma unroll
;     for (int ai = 0; ai < 2; ++ai)
; #pragma unroll
;         for (int m = 0; m < 4; ++m) { const float* p = ssq + (size_t)(4 * fq) * 16384 + row0 + ai * HALF + m * 16;
; #pragma unroll
;             for (int k = 0; k < 4; ++k) v[ai][m][k] = ld_agent(p + k * 16384); }
;     ...
;     if constexpr (Epi::ROWSCALE) { float rr0[2][4]; row_rs8(E.ssq, cur.pm * BM + wr * 64 + fr, fq, rr0);
; #pragma unroll
;         for (int m = 0; m < 4; ++m) rrp[m] = __builtin_amdgcn_cvt_pkrtz(rr0[0][m], rr0[1][m]); }
;     const char* cA = (const char*)gA + (size_t)cur.pm * tstepA + (size_t)cur.pn * acolB; const char* cB = (const char*)gB + (size_t)cur.pn * tstepB;
;     S.a_ready(cur);
;     if constexpr (SP2) {
;         PG8_STAGE(PG8_SB(0, 0), cB, voffB); PG8_STAGE(PG8_SB(0, 1), cB + hstepB, voffB); PG8_STAGE(PG8_SA(0, 0), cA, voffA); PG8_STAGE(PG8_SA(0, 1), cA + hstepA, voffA);
.LBB0_598:
	s_cmp_le_i32 s56, s0
	s_cselect_b64 s[2:3], -1, 0
	s_and_b64 s[42:43], s[2:3], s[6:7]
	s_andn2_b64 vcc, exec, s[42:43]
	s_cbranch_vccnz .LBB0_679
	v_readlane_b32 s0, v254, 52
	s_mul_i32 s0, s0, 0x580000
	s_lshl_b64 s[2:3], s[0:1], 1
	v_readlane_b32 s0, v253, 47
	s_add_u32 s4, s0, s2
	v_readlane_b32 s0, v253, 48
	s_addc_u32 s5, s0, s3
	v_readlane_b32 s2, v253, 49
	v_mov_b32_e32 v2, v0
	v_readlane_b32 s3, v253, 50
	s_movk_i32 s6, 0x400
	v_readfirstlane_b32 s19, v2
	s_mov_b64 s[44:45], s[84:85]
	s_andn2_b64 vcc, exec, s[2:3]
	s_cbranch_vccnz .LBB0_620
	s_waitcnt lgkmcnt(0)
	v_lshlrev_b32_e32 v3, 4, v2
	v_add_u32_e32 v4, 0x2000, v3
	v_ashrrev_i32_e32 v5, 31, v4
	v_lshrrev_b32_e32 v5, 22, v5
	v_add_u32_e32 v5, v4, v5
	v_ashrrev_i32_e32 v5, 10, v5
	v_mul_i32_i24_e32 v6, 0x400, v5
	v_sub_u32_e32 v4, v4, v6
	v_lshrrev_b32_e32 v6, 4, v4
	v_bitop3_b32 v4, v6, v4, 32 bitop3:0x6c
	v_ashrrev_i32_e32 v6, 31, v4
	v_lshrrev_b32_e32 v6, 26, v6
	v_add_u32_e32 v6, v4, v6
	v_lshlrev_b32_e32 v8, 3, v5
	v_ashrrev_i32_e32 v7, 6, v6
	v_and_b32_e32 v8, -16, v8
	v_lshlrev_b32_e32 v5, 5, v5
	v_add_u32_e32 v8, v7, v8
	v_and_b32_e32 v15, 32, v5
	v_and_b32_e32 v5, 0xc0, v6
	v_and_b32_e32 v7, 3, v7
	s_mov_b32 s3, 0x7fffffe0
	v_lshrrev_b32_e32 v9, 2, v8
	v_lshlrev_b32_e32 v10, 1, v8
	v_sub_u32_e32 v4, v4, v5
	v_and_or_b32 v7, v8, s3, v7
	v_and_b32_e32 v9, 4, v9
	v_and_b32_e32 v10, 24, v10
	v_ashrrev_i16_sdwa v4, v243, sext(v4) dst_sel:DWORD dst_unused:UNUSED_PAD src0_sel:DWORD src1_sel:BYTE_0
	v_or3_b32 v7, v7, v9, v10
	v_bfe_i32 v16, v4, 0, 16
	v_mul_lo_u32 v7, v7, s6
	v_add_u32_e32 v4, v15, v16
	v_mul_lo_u32 v17, v8, s6
	v_add_lshl_u32 v130, v7, v4, 1
	v_add_lshl_u32 v132, v4, v17, 1
	v_bfe_i32 v4, v2, 27, 1
	v_lshrrev_b32_e32 v4, 22, v4
	v_add_u32_e32 v4, v3, v4
	v_and_b32_e32 v4, 0xfffffc00, v4
	v_sub_u32_e32 v3, v3, v4
	v_lshrrev_b32_e32 v4, 4, v3
	v_ashrrev_i32_e32 v6, 31, v2
	v_bitop3_b32 v3, v4, v3, 32 bitop3:0x6c
	v_lshrrev_b32_e32 v6, 26, v6
	v_and_b32_e32 v141, 15, v2
	v_bfe_u32 v14, v2, 4, 2
	v_ashrrev_i32_e32 v4, 31, v3
	v_add_u32_e32 v2, v2, v6
	v_lshrrev_b32_e32 v4, 26, v4
	v_ashrrev_i32_e32 v2, 6, v2
	v_add_u32_e32 v4, v3, v4
	v_lshlrev_b32_e32 v6, 3, v2
	v_ashrrev_i32_e32 v5, 6, v4
	v_and_b32_e32 v6, -16, v6
	v_lshlrev_b32_e32 v2, 5, v2
	v_add_u32_e32 v6, v5, v6
	v_and_b32_e32 v18, 32, v2
	v_and_b32_e32 v2, 0xc0, v4
	v_and_b32_e32 v5, 3, v5
	v_lshrrev_b32_e32 v7, 2, v6
	v_lshlrev_b32_e32 v8, 1, v6
	v_sub_u32_e32 v2, v3, v2
	s_ashr_i32 s17, s19, 8
	v_and_or_b32 v5, v6, s3, v5
	v_and_b32_e32 v7, 4, v7
	v_and_b32_e32 v8, 24, v8
	v_ashrrev_i16_sdwa v2, v243, sext(v2) dst_sel:DWORD dst_unused:UNUSED_PAD src0_sel:DWORD src1_sel:BYTE_0
	s_lshl_b32 s2, s17, 6
	v_or3_b32 v5, v5, v7, v8
	v_bfe_i32 v19, v2, 0, 16
	v_readlane_b32 s3, v254, 20
	v_mul_lo_u32 v5, v5, s6
	v_add_u32_e32 v2, v18, v19
	v_mul_lo_u32 v20, v6, s6
	s_add_i32 s3, s3, s2
	v_readlane_b32 s8, v252, 15
	v_add_lshl_u32 v8, v5, v2, 1
	v_add_lshl_u32 v134, v2, v20, 1
	v_or_b32_e32 v2, s3, v141
	v_lshlrev_b32_e32 v166, 18, v14
	v_readlane_b32 s9, v252, 16
	v_ashrrev_i32_e32 v3, 31, v2
	s_mov_b32 s3, 0x10000
	v_lshl_add_u64 v[4:5], s[8:9], 0, v[166:167]
	v_lshl_add_u64 v[2:3], v[2:3], 2, v[4:5]
	v_add_co_u32_e32 v4, vcc, s3, v2
	s_mov_b32 s3, 0x20000
	s_nop 0
	v_addc_co_u32_e32 v5, vcc, 0, v3, vcc
	v_add_co_u32_e32 v6, vcc, s3, v2
	global_load_dword v9, v[2:3], off
	global_load_dword v12, v[4:5], off
	v_addc_co_u32_e32 v7, vcc, 0, v3, vcc
	global_load_dword v13, v[6:7], off
	s_mov_b32 s3, 0x30000
	v_add_co_u32_e32 v10, vcc, s3, v2
	s_ashr_i32 s7, s6, 31
	s_nop 0
	v_addc_co_u32_e32 v11, vcc, 0, v3, vcc
	global_load_dword v21, v[10:11], off
	global_load_dword v23, v[2:3], off offset:64
	global_load_dword v24, v[4:5], off offset:64
	global_load_dword v25, v[6:7], off offset:64
	global_load_dword v26, v[10:11], off offset:64
	global_load_dword v27, v[2:3], off offset:128
	global_load_dword v28, v[4:5], off offset:128
	global_load_dword v29, v[6:7], off offset:128
	global_load_dword v30, v[10:11], off offset:128
	global_load_dword v31, v[2:3], off offset:192
	global_load_dword v32, v[4:5], off offset:192
	global_load_dword v33, v[6:7], off offset:192
	global_load_dword v34, v[10:11], off offset:192
	global_load_dword v35, v[2:3], off offset:512
	global_load_dword v36, v[4:5], off offset:512
	global_load_dword v37, v[6:7], off offset:512
	global_load_dword v38, v[10:11], off offset:512
	global_load_dword v39, v[2:3], off offset:576
	global_load_dword v40, v[4:5], off offset:576
	global_load_dword v41, v[6:7], off offset:576
	global_load_dword v42, v[10:11], off offset:576
	global_load_dword v43, v[2:3], off offset:640
	global_load_dword v44, v[4:5], off offset:640
	global_load_dword v45, v[6:7], off offset:640
	global_load_dword v46, v[10:11], off offset:640
	s_nop 0
	global_load_dword v2, v[2:3], off offset:704
	s_nop 0
	global_load_dword v3, v[4:5], off offset:704
	s_nop 0
	global_load_dword v4, v[6:7], off offset:704
	global_load_dword v5, v[10:11], off offset:704
	v_and_b32_e32 v7, 64, v242
	v_xor_b32_e32 v6, 16, v242
	v_add_u32_e32 v7, 64, v7
	v_cmp_lt_i32_e32 vcc, v6, v7
	v_xor_b32_e32 v10, 32, v242
	s_lshl_b64 s[60:61], s[6:7], 9
	v_cndmask_b32_e32 v6, v242, v6, vcc
	v_cmp_lt_i32_e32 vcc, v10, v7
	v_lshlrev_b32_e32 v6, 2, v6
	v_readlane_b32 s3, v254, 22
	v_cndmask_b32_e32 v7, v242, v10, vcc
	v_readlane_b32 s10, v254, 21
	s_mul_i32 s3, s60, s3
	s_mul_hi_u32 s8, s60, s10
	s_add_i32 s3, s8, s3
	s_lshr_b64 s[8:9], s[6:7], 23
	s_mul_i32 s9, s8, s10
	s_mul_i32 s13, s60, s10
	v_readlane_b32 s10, v254, 15
	v_readlane_b32 s11, v254, 16
	s_add_i32 s12, s3, s9
	s_mul_i32 s3, s60, s11
	s_mul_hi_u32 s9, s60, s10
	s_ashr_i32 s16, s19, 6
	s_add_i32 s3, s9, s3
	s_mul_i32 s8, s8, s10
	s_lshl_b64 s[58:59], s[6:7], 8
	s_lshl_b32 s0, s16, 10
	s_add_i32 s3, s3, s8
	s_mul_i32 s8, s60, s10
	s_add_u32 s8, s4, s8
	s_addc_u32 s9, s5, s3
	s_add_i32 s3, s0, 0
	s_add_i32 m0, s3, 0x10000
	v_lshlrev_b32_e32 v7, 2, v7
	global_load_lds_dwordx4 v8, s[8:9]
	s_add_i32 m0, s3, 0x12000
	s_add_u32 s10, s8, s58
	global_load_lds_dwordx4 v130, s[8:9]
	s_addc_u32 s11, s9, s59
	s_add_i32 m0, s3, 0x14000
	v_mov_b32_e32 v166, v8
	v_mov_b32_e32 v131, v167
	global_load_lds_dwordx4 v8, s[10:11]
	s_add_i32 m0, s3, 0x16000
	v_mov_b32_e32 v135, v167
	global_load_lds_dwordx4 v130, s[10:11]
	s_mov_b32 m0, s3
	v_mov_b32_e32 v133, v167
	s_add_u32 s22, s44, s13
	s_addc_u32 s23, s45, s12
	s_add_u32 s56, s22, s58
	s_addc_u32 s57, s23, s59
	global_load_lds_dwordx4 v134, s[22:23]
	s_add_i32 m0, s3, 0x2000
	s_nop 0
	global_load_lds_dwordx4 v132, s[22:23]
	s_add_i32 m0, s3, 0x4000
	s_nop 0
	global_load_lds_dwordx4 v134, s[56:57]
	s_add_i32 m0, s3, 0x6000
	s_nop 0
	global_load_lds_dwordx4 v132, s[56:57]
	s_waitcnt vmcnt(8)
; #define PG8_STAGE(bufoff, gbase, voff) do { _Pragma("unroll") for (int _i = 0; _i < 2; ++_i) \
;         __builtin_amdgcn_global_load_lds((const unsigned*)((const char*)(gbase) + (voff)[_i]), (PG8_LAS unsigned*)(lds + (bufoff) + ldsw + _i * 8192), 16, 0, 0); } while (0)
; #define PG8_BAR __builtin_amdgcn_s_barrier()
; __device__ __forceinline__ void row_rs8(const float* ssq, int row0, int fq, float (&rr)[2][4]) {
;     ...
;         for (int m = 0; m < 4; ++m) { float s = (v[ai][m][0] + v[ai][m][1]) + (v[ai][m][2] + v[ai][m][3]);
;             s += __shfl_xor(s, 16); s += __shfl_xor(s, 32); rr[ai][m] = __builtin_amdgcn_rsqf(s * (1.0f / 1024.0f) + RMS_EPS); }
;     ...
;         PG8_STAGE(PG8_SB(0, 0), cB, voffB); PG8_STAGE(PG8_SB(0, 1), cB + hstepB, voffB); PG8_STAGE(PG8_SA(0, 0), cA, voffA); PG8_STAGE(PG8_SA(0, 1), cA + hstepA, voffA);
;         if (wr == 1) PG8_BAR;
	v_add_f32_e32 v9, v9, v12
	v_add_f32_e32 v10, v13, v21
	v_add_f32_e32 v9, v9, v10
	ds_bpermute_b32 v10, v6, v9
	v_add_f32_e32 v2, v2, v3
	s_waitcnt lgkmcnt(0)
	v_add_f32_e32 v21, v9, v10
	v_add_f32_e32 v9, v23, v24
	v_add_f32_e32 v10, v25, v26
	v_add_f32_e32 v9, v9, v10
	ds_bpermute_b32 v10, v6, v9
	v_add_f32_e32 v3, v4, v5
	v_add_f32_e32 v2, v2, v3
	ds_bpermute_b32 v3, v6, v2
	ds_bpermute_b32 v22, v7, v21
	s_waitcnt lgkmcnt(2)
	v_add_f32_e32 v23, v9, v10
	v_add_f32_e32 v9, v27, v28
	v_add_f32_e32 v10, v29, v30
	v_add_f32_e32 v9, v9, v10
	ds_bpermute_b32 v10, v6, v9
	ds_bpermute_b32 v24, v7, v23
	v_lshl_add_u64 v[4:5], s[8:9], 0, v[130:131]
	s_waitcnt lgkmcnt(1)
	v_add_f32_e32 v25, v9, v10
	v_add_f32_e32 v9, v31, v32
	v_add_f32_e32 v10, v33, v34
	v_add_f32_e32 v9, v9, v10
	ds_bpermute_b32 v10, v6, v9
	ds_bpermute_b32 v26, v7, v25
	s_waitcnt lgkmcnt(1)
	v_add_f32_e32 v27, v9, v10
	v_add_f32_e32 v9, v35, v36
	v_add_f32_e32 v10, v37, v38
	v_add_f32_e32 v9, v9, v10
	ds_bpermute_b32 v10, v6, v9
	v_add_f32_e32 v35, v2, v3
	ds_bpermute_b32 v28, v7, v27
	ds_bpermute_b32 v36, v7, v35
	v_lshl_add_u64 v[2:3], s[8:9], 0, v[166:167]
	s_waitcnt lgkmcnt(2)
	v_add_f32_e32 v29, v9, v10
	v_add_f32_e32 v9, v39, v40
	v_add_f32_e32 v10, v41, v42
	v_add_f32_e32 v9, v9, v10
	ds_bpermute_b32 v10, v6, v9
	ds_bpermute_b32 v30, v7, v29
	s_waitcnt lgkmcnt(1)
	v_add_f32_e32 v31, v9, v10
	v_add_f32_e32 v9, v43, v44
	v_add_f32_e32 v10, v45, v46
	v_add_f32_e32 v9, v9, v10
	ds_bpermute_b32 v10, v6, v9
	ds_bpermute_b32 v32, v7, v31
	s_waitcnt lgkmcnt(1)
	v_add_f32_e32 v33, v9, v10
	ds_bpermute_b32 v34, v7, v33
	v_lshl_add_u64 v[6:7], s[10:11], 0, v[166:167]
	v_lshl_add_u64 v[8:9], s[10:11], 0, v[130:131]
	s_add_u32 s10, s44, s13
	s_addc_u32 s11, s45, s12
	s_add_i32 s12, s3, 0x2000
	s_add_u32 s20, s10, s58
	s_addc_u32 s21, s11, s59
	s_add_i32 s13, s3, 0x4000
	s_add_i32 s14, s3, 0x6000
	s_cmp_eq_u32 s17, 1
	v_lshl_add_u64 v[10:11], s[10:11], 0, v[134:135]
	v_lshl_add_u64 v[12:13], s[10:11], 0, v[132:133]
	s_cselect_b64 s[72:73], -1, 0
	s_cmp_lg_u32 s17, 1
	s_cbranch_scc1 .LBB0_602
	s_barrier
